# v37 + P3/P8/P11: odd workgroups run their sample-row GEMM item before the main unit (even after), staggering the residual epilogues
# speedup vs baseline: 1.0150x; 1.0059x over previous
.Lsg3_redo:
	s_add_u32 s12, s74, 0xc00000
	s_addc_u32 s13, s75, 0
	s_add_u32 s10, s74, 0x2000
	s_addc_u32 s11, s75, 0
	s_cmp_eq_u32 s100, 2
	s_cbranch_scc1 .Lsg3_main
	s_cmpk_lg_i32 s78, 0x100
	s_cbranch_scc1 .Lsg3_main
	s_bitcmp1_b32 s97, 0
	s_cbranch_scc0 .Lsg3_main
	s_mov_b32 s100, 1
	s_branch .LBB0_336

.LBB0_1011:
	s_mov_b32 s100, 0
	s_cmp_lt_i32 s76, 9
	s_cselect_b64 s[0:1], -1, 0
	s_cmp_gt_i32 s77, 8
	s_cselect_b64 s[2:3], -1, 0
	s_and_b64 s[0:1], s[0:1], s[2:3]
	s_andn2_b64 vcc, exec, s[0:1]
	s_cbranch_vccnz .LBB0_1089
.Lsg8_redo:
	s_add_u32 s6, s72, 0x4000000
	s_addc_u32 s7, s73, 0
	s_add_u32 s10, s74, 0x5000
	s_addc_u32 s11, s75, 0
	v_readlane_b32 s2, v246, 46
	s_cmp_eq_u32 s100, 2
	s_cbranch_scc1 .Lsg8_main
	s_cmpk_lg_i32 s78, 0x100
	s_cbranch_scc1 .Lsg8_main
	s_bitcmp1_b32 s97, 0
	s_cbranch_scc0 .Lsg8_main
	s_mov_b32 s100, 1
	s_branch .LBB0_1040
.Lsg8_main:
	s_cmpk_lt_i32 s2, 0x100
	s_cselect_b64 s[8:9], -1, 0
	s_cmpk_gt_i32 s2, 0xff
	v_readfirstlane_b32 s28, v236
	s_cbranch_scc1 .LBB0_1040
	v_readlane_b32 s3, v246, 46
	s_ashr_i32 s29, s3, 31
	s_lshr_b32 s2, s29, 29
	s_add_i32 s5, s3, s2
	s_and_b32 s2, s5, -8
	s_sub_i32 s12, s3, s2
	s_cmp_gt_i32 s12, -1
	s_cbranch_scc0 .LBB0_1015
	s_lshl_b32 s4, s12, 5
	s_cbranch_execz .LBB0_1016
	s_branch .LBB0_1017

.LBB0_1040:
	v_mov_b32_e32 v0, v236
	s_cmp_eq_u32 s100, 2
	s_cbranch_scc1 .Lsg8_skip
	s_cmpk_gt_i32 s97, 0xff
	s_cbranch_scc1 .LBB0_1045
	v_and_b32_e32 v94, 15, v0
	v_ashrrev_i32_e32 v5, 6, v0
	v_lshrrev_b32_e32 v1, 4, v0
	v_bfe_u32 v4, v0, 4, 2
	v_lshlrev_b32_e32 v2, 7, v5
	v_ashrrev_i32_e32 v95, 3, v0
	v_and_b32_e32 v0, 7, v0
	v_lshlrev_b32_e32 v5, 14, v5
	v_lshlrev_b32_e32 v6, 8, v94
	v_lshlrev_b32_e32 v96, 3, v0
	v_add3_u32 v5, 0, v5, v6
	v_lshlrev_b32_e32 v0, 1, v0
	v_and_b32_e32 v6, 15, v95
	v_bitop3_b32 v7, v0, v95, 15 bitop3:0x78
	v_bitop3_b32 v0, v0, v6, 1 bitop3:0x36
	v_lshlrev_b32_e32 v98, 4, v7
	v_lshlrev_b32_e32 v99, 4, v0
	v_bitop3_b32 v0, v1, v94, 3 bitop3:0x6c
	v_bitop3_b32 v1, v4, v94, 4 bitop3:0x36
	v_bitop3_b32 v6, v4, v94, 8 bitop3:0x36
	v_bitop3_b32 v7, v4, v94, 12 bitop3:0x36
	v_ashrrev_i32_e32 v3, 31, v2
	v_lshl_add_u32 v97, v95, 8, 0
	v_lshlrev_b32_e32 v0, 4, v0
	v_lshlrev_b32_e32 v1, 4, v1
	v_lshlrev_b32_e32 v6, 4, v6
	v_lshlrev_b32_e32 v7, 4, v7
	v_lshlrev_b32_e32 v82, 4, v4
	v_mov_b32_e32 v83, 0
	v_add_u32_e32 v100, 0x10000, v97
	v_add_u32_e32 v101, 0x14000, v97
	v_add_u32_e32 v102, 0x18000, v97
	v_add_u32_e32 v103, 0x1c000, v97
	v_lshlrev_b64 v[80:81], 1, v[2:3]
	v_lshl_add_u64 v[84:85], s[74:75], 0, v[82:83]
	s_lshl_b32 s4, s97, 2
	s_lshl_b32 s5, s78, 2
	v_lshlrev_b32_e32 v104, 10, v94
	s_lshl_b32 s12, s97, 6
	s_lshl_b32 s13, s78, 6
	s_mov_b32 s14, 0x9000
	v_mov_b64_e32 v[86:87], s[10:11]
	s_mov_b32 s10, 0x5600000
	s_mov_b32 s11, 0x2300000
	s_mov_b32 s15, 0x5608000
	s_mov_b32 s16, 0x2308000
	s_mov_b32 s17, 0x5610000
	s_mov_b32 s18, 0x2310000
	s_mov_b32 s19, 0x5618000
	s_mov_b32 s20, 0x2318000
	s_mov_b64 s[2:3], 0x80
	v_add_u32_e32 v105, v5, v0
	v_add_u32_e32 v106, v5, v1
	v_add_u32_e32 v107, v5, v6
	v_add_u32_e32 v108, v5, v7
	s_mov_b32 s21, s97

.Lsg8_skip:
.LBB0_1045:
	s_cmp_eq_u32 s100, 1
	s_cbranch_scc0 .Lsg8_cont
	s_mov_b32 s100, 2
	s_branch .Lsg8_redo

.LBB0_1297:
	s_mov_b32 s100, 0
	s_cmp_lt_i32 s76, 12
	s_cselect_b64 s[0:1], -1, 0
	s_and_b64 s[0:1], s[0:1], s[2:3]
	s_andn2_b64 vcc, exec, s[0:1]
	s_cbranch_vccnz .LBB0_1377
.Lsg11_redo:
	s_add_u32 s14, s74, 0x3000000
	s_addc_u32 s15, s75, 0
	s_add_u32 s8, s72, 0x4000000
	s_addc_u32 s9, s73, 0
	s_add_u32 s12, s74, 0x8000
	s_addc_u32 s13, s75, 0
	s_cmp_eq_u32 s100, 2
	s_cbranch_scc1 .Lsg11_main
	s_cmpk_lg_i32 s78, 0x100
	s_cbranch_scc1 .Lsg11_main
	s_bitcmp1_b32 s97, 0
	s_cbranch_scc0 .Lsg11_main
	s_mov_b32 s100, 1
	s_branch .LBB0_1330
.Lsg11_main:
	s_cmpk_lt_i32 s50, 0x100
	s_cselect_b64 s[10:11], -1, 0
	s_cmpk_gt_i32 s50, 0xff
	v_readfirstlane_b32 s26, v236
	s_cbranch_scc1 .LBB0_1330
	s_ashr_i32 s27, s50, 31
	s_lshr_b32 s2, s27, 29
	s_add_i32 s5, s50, s2
	s_and_b32 s2, s5, -8
	s_sub_i32 s6, s50, s2
	s_cmp_gt_i32 s6, -1
	s_cbranch_scc0 .LBB0_1301
	s_lshl_b32 s4, s6, 5
	s_cbranch_execz .LBB0_1302
	s_branch .LBB0_1303

.LBB0_1330:
	v_mov_b32_e32 v0, v236
	s_cmp_eq_u32 s100, 2
	s_cbranch_scc1 .Lsg11_skip
	s_cmpk_gt_i32 s97, 0xff
	s_cbranch_scc1 .LBB0_1333
	v_ashrrev_i32_e32 v7, 6, v0
	s_movk_i32 s2, 0x160
	v_mul_lo_u32 v2, v7, s2
	v_ashrrev_i32_e32 v3, 31, v2
	v_bfe_u32 v6, v0, 4, 2
	v_lshlrev_b64 v[2:3], 1, v[2:3]
	v_and_b32_e32 v58, 15, v0
	v_lshl_add_u64 v[4:5], s[74:75], 0, v[2:3]
	v_lshlrev_b32_e32 v36, 4, v6
	v_mov_b32_e32 v37, 0
	v_lshl_add_u64 v[2:3], s[14:15], 0, v[2:3]
	v_lshrrev_b32_e32 v1, 4, v0
	v_lshl_add_u64 v[40:41], v[2:3], 0, v[36:37]
	v_ashrrev_i32_e32 v59, 3, v0
	v_and_b32_e32 v0, 7, v0
	v_lshlrev_b32_e32 v2, 14, v7
	v_lshlrev_b32_e32 v3, 8, v58
	v_lshl_add_u64 v[4:5], v[4:5], 0, v[36:37]
	s_mov_b64 s[2:3], 0xb000000
	v_lshlrev_b32_e32 v60, 3, v0
	v_add3_u32 v2, 0, v2, v3
	v_lshlrev_b32_e32 v0, 1, v0
	v_and_b32_e32 v3, 15, v59
	v_lshl_add_u64 v[38:39], v[4:5], 0, s[2:3]
	v_bitop3_b32 v4, v0, v59, 15 bitop3:0x78
	v_bitop3_b32 v0, v0, v3, 1 bitop3:0x36
	v_lshl_add_u32 v3, v59, 8, 0
	v_bitop3_b32 v1, v1, v58, 3 bitop3:0x6c
	v_bitop3_b32 v5, v6, v58, 4 bitop3:0x36
	v_bitop3_b32 v7, v6, v58, 8 bitop3:0x36
	v_bitop3_b32 v6, v6, v58, 12 bitop3:0x36
	v_lshlrev_b32_e32 v4, 4, v4
	v_lshlrev_b32_e32 v0, 4, v0
	v_lshlrev_b32_e32 v1, 4, v1
	v_lshlrev_b32_e32 v5, 4, v5
	v_lshlrev_b32_e32 v7, 4, v7
	v_lshlrev_b32_e32 v6, 4, v6
	v_add_u32_e32 v8, 0x10000, v3
	v_add_u32_e32 v9, 0x14000, v3
	v_add_u32_e32 v10, 0x18000, v3
	v_add_u32_e32 v11, 0x1c000, v3
	s_lshl_b32 s2, s97, 6
	s_lshl_b32 s3, s78, 6
	s_lshl_b32 s4, s97, 2
	s_lshl_b32 s5, s78, 2
	s_mov_b32 s6, 0x9000
	v_mov_b64_e32 v[42:43], s[12:13]
	s_movk_i32 s7, 0x1600
	s_mov_b32 s12, 0x16000
	s_mov_b32 s13, 0x2c000
	s_mov_b32 s14, 0x42000
	v_add_u32_e32 v61, v2, v1
	v_add_u32_e32 v62, v2, v5
	v_add_u32_e32 v63, v2, v7
	v_add_u32_e32 v64, v2, v6
	v_add_u32_e32 v65, v3, v4
	v_add_u32_e32 v66, v3, v0
	v_add_u32_e32 v67, v8, v4
	v_add_u32_e32 v68, v8, v0
	v_add_u32_e32 v69, v9, v4
	v_add_u32_e32 v70, v9, v0
	v_add_u32_e32 v71, v10, v4
	v_add_u32_e32 v72, v10, v0
	v_add_u32_e32 v73, v11, v4
	v_add_u32_e32 v74, v11, v0
	s_mov_b32 s15, s97
